# F5 EpiBranch: gate tile g(k+1) carried in VGPRs to the next sub-unit (12 of 16 pairs), 24 fewer gate loads per tile
# speedup vs baseline: 1.0070x; 1.0070x over previous
.LBB0_971:
	s_cmp_eq_u32 s7, 0
	s_cselect_b64 s[100:101], -1, 0
	v_lshl_or_b32 v140, s8, 8, v212
	v_ashrrev_i32_e32 v141, 31, v140
	v_lshl_add_u32 v142, s6, 8, v210
	v_lshl_add_u64 v[144:145], s[16:17], 0, v[140:141]
	s_lshl_b32 s24, s7, 11
	s_ashr_i32 s25, s24, 31
	v_mad_i64_i32 v[146:147], s[8:9], v142, s97, v[144:145]
	v_lshl_add_u64 v[146:147], v[146:147], 0, s[24:25]
	s_and_b64 vcc, exec, s[100:101]
	s_cbranch_vccz .Lcarry5_0
	global_load_dwordx2 v[190:191], v[146:147], off
.Lcarry5_0:
	s_cmp_eq_u32 s7, 2
	s_cselect_b64 s[26:27], -1, 0
	s_cmp_lg_u32 s7, 2
	s_cselect_b64 s[22:23], -1, 0
	v_mov_b32_e32 v178, 0
	s_and_b64 vcc, exec, s[26:27]
	v_mov_b32_e32 v186, 0
	v_mov_b32_e32 v187, 0
	s_cbranch_vccnz .LBB0_973
	global_load_dwordx2 v[186:187], v[146:147], off offset:2048
.LBB0_973:
	s_and_b64 vcc, exec, s[100:101]
	s_cbranch_vccz .Lcarry5_1
	global_load_dwordx2 v[182:183], v[146:147], off offset:128
.Lcarry5_1:
	v_cndmask_b32_e64 v143, 0, 1, s[22:23]
	v_cmp_ne_u32_e64 s[6:7], 1, v143
	s_andn2_b64 vcc, exec, s[22:23]
	v_mov_b32_e32 v179, 0
	s_cbranch_vccnz .LBB0_975
	global_load_dwordx2 v[178:179], v[146:147], off offset:2176
.LBB0_975:
	v_or_b32_e32 v156, 16, v142
	v_mad_i64_i32 v[146:147], s[8:9], v156, s97, v[144:145]
	v_lshl_add_u64 v[146:147], v[146:147], 0, s[24:25]
	s_and_b64 vcc, exec, s[100:101]
	s_cbranch_vccz .Lcarry5_2
	global_load_dwordx2 v[174:175], v[146:147], off
.Lcarry5_2:
	v_ashrrev_i32_e32 v143, 31, v142
	v_mov_b32_e32 v148, 0
	s_and_b64 vcc, exec, s[6:7]
	v_mov_b32_e32 v160, 0
	v_mov_b32_e32 v161, 0
	s_cbranch_vccnz .LBB0_977
	global_load_dwordx2 v[160:161], v[146:147], off offset:2048
.LBB0_977:
	s_and_b64 vcc, exec, s[100:101]
	s_cbranch_vccz .Lcarry5_3
	global_load_dwordx2 v[152:153], v[146:147], off offset:128
.Lcarry5_3:
	s_and_b64 vcc, exec, s[6:7]
	v_mov_b32_e32 v149, 0
	s_cbranch_vccnz .LBB0_979
	global_load_dwordx2 v[148:149], v[146:147], off offset:2176
.LBB0_979:
	v_or_b32_e32 v184, 32, v142
	v_mad_i64_i32 v[146:147], s[8:9], v184, s97, v[144:145]
	v_lshl_add_u64 v[146:147], v[146:147], 0, s[24:25]
	s_and_b64 vcc, exec, s[100:101]
	s_cbranch_vccz .Lcarry5_4
	global_load_dwordx2 v[192:193], v[146:147], off
.Lcarry5_4:
	v_mov_b32_e32 v176, 0
	s_and_b64 vcc, exec, s[6:7]
	v_mov_b32_e32 v188, 0
	v_mov_b32_e32 v189, 0
	s_cbranch_vccnz .LBB0_981
	global_load_dwordx2 v[188:189], v[146:147], off offset:2048
.LBB0_981:
	s_and_b64 vcc, exec, s[100:101]
	s_cbranch_vccz .Lcarry5_5
	global_load_dwordx2 v[180:181], v[146:147], off offset:128
.Lcarry5_5:
	s_and_b64 vcc, exec, s[6:7]
	v_mov_b32_e32 v177, 0
	s_cbranch_vccnz .LBB0_983
	global_load_dwordx2 v[176:177], v[146:147], off offset:2176
.LBB0_983:
	v_or_b32_e32 v154, 48, v142
	v_mad_i64_i32 v[146:147], s[8:9], v154, s97, v[144:145]
	v_lshl_add_u64 v[194:195], v[146:147], 0, s[24:25]
	s_and_b64 vcc, exec, s[100:101]
	s_cbranch_vccz .Lcarry5_6
	global_load_dwordx2 v[172:173], v[194:195], off
.Lcarry5_6:
	v_mov_b32_e32 v146, 0
	s_and_b64 vcc, exec, s[6:7]
	v_mov_b32_e32 v158, 0
	v_mov_b32_e32 v159, 0
	s_cbranch_vccnz .LBB0_985
	global_load_dwordx2 v[158:159], v[194:195], off offset:2048
.LBB0_985:
	s_and_b64 vcc, exec, s[100:101]
	s_cbranch_vccz .Lcarry5_7
	global_load_dwordx2 v[150:151], v[194:195], off offset:128
.Lcarry5_7:
	s_and_b64 vcc, exec, s[6:7]
	v_mov_b32_e32 v147, 0
	s_cbranch_vccnz .LBB0_987
	global_load_dwordx2 v[146:147], v[194:195], off offset:2176
.LBB0_987:
	s_waitcnt vmcnt(0)
	v_cndmask_b32_e64 v190, v230, v190, s[100:101]
	v_cndmask_b32_e64 v191, v231, v191, s[100:101]
	v_cvt_f32_ubyte1_e32 v195, v190
	v_cvt_f32_ubyte0_e32 v194, v190
	v_cvt_f32_ubyte3_e32 v197, v190
	v_cvt_f32_ubyte2_e32 v196, v190
	v_cvt_f32_ubyte1_e32 v201, v191
	v_cvt_f32_ubyte0_e32 v200, v191
	v_cvt_f32_ubyte3_e32 v203, v191
	v_cvt_f32_ubyte2_e32 v202, v191
	s_mov_b64 s[8:9], -1
	s_and_b64 vcc, exec, s[22:23]
	s_cbranch_vccz .LBB0_989
	v_mov_b32_e32 v230, v186
	v_mov_b32_e32 v231, v187
	v_cvt_f32_ubyte0_e32 v155, v186
	v_cvt_f32_ubyte1_e32 v157, v186
	v_cvt_f32_ubyte2_e32 v170, v186
	v_cvt_f32_ubyte3_e32 v171, v186
	v_cvt_f32_ubyte0_e32 v185, v187
	v_cvt_f32_ubyte1_e32 v190, v187
	v_cvt_f32_ubyte2_e32 v191, v187
	v_cvt_f32_ubyte3_e32 v199, v187
	v_rcp_iflag_f32_e32 v168, v155
	v_rcp_iflag_f32_e32 v169, v157
	v_rcp_iflag_f32_e32 v170, v170
	v_rcp_iflag_f32_e32 v171, v171
	v_rcp_iflag_f32_e32 v186, v185
	v_rcp_iflag_f32_e32 v187, v190
	v_rcp_iflag_f32_e32 v198, v191
	v_rcp_iflag_f32_e32 v199, v199
	v_pk_mul_f32 v[204:205], v[168:169], v[194:195]
	v_pk_mul_f32 v[206:207], v[170:171], v[196:197]
	v_pk_mul_f32 v[190:191], v[186:187], v[200:201]
	v_pk_mul_f32 v[198:199], v[198:199], v[202:203]
	s_mov_b64 s[8:9], 0

.LBB0_993:
	v_cndmask_b32_e64 v182, v232, v182, s[100:101]
	v_cndmask_b32_e64 v183, v233, v183, s[100:101]
	v_cvt_f32_ubyte1_e32 v191, v182
	v_cvt_f32_ubyte0_e32 v190, v182
	v_cvt_f32_ubyte3_e32 v195, v182
	v_cvt_f32_ubyte2_e32 v194, v182
	v_cvt_f32_ubyte1_e32 v197, v183
	v_cvt_f32_ubyte0_e32 v196, v183
	v_cvt_f32_ubyte3_e32 v201, v183
	v_cvt_f32_ubyte2_e32 v200, v183
	s_and_b64 vcc, exec, s[6:7]
	s_mov_b64 s[26:27], -1
	s_cbranch_vccnz .LBB0_995
	v_mov_b32_e32 v232, v178
	v_mov_b32_e32 v233, v179
	v_cvt_f32_ubyte0_e32 v143, v178
	v_cvt_f32_ubyte1_e32 v155, v178
	v_cvt_f32_ubyte2_e32 v157, v178
	v_cvt_f32_ubyte3_e32 v171, v178
	v_cvt_f32_ubyte0_e32 v178, v179
	v_cvt_f32_ubyte1_e32 v182, v179
	v_cvt_f32_ubyte2_e32 v183, v179
	v_cvt_f32_ubyte3_e32 v185, v179
	v_rcp_iflag_f32_e32 v168, v143
	v_rcp_iflag_f32_e32 v169, v155
	v_rcp_iflag_f32_e32 v170, v157
	v_rcp_iflag_f32_e32 v171, v171
	v_rcp_iflag_f32_e32 v178, v178
	v_rcp_iflag_f32_e32 v179, v182
	v_rcp_iflag_f32_e32 v198, v183
	v_rcp_iflag_f32_e32 v199, v185
	v_pk_mul_f32 v[202:203], v[168:169], v[190:191]
	v_pk_mul_f32 v[204:205], v[170:171], v[194:195]
	v_pk_mul_f32 v[182:183], v[178:179], v[196:197]
	v_pk_mul_f32 v[198:199], v[198:199], v[200:201]
	s_mov_b64 s[26:27], 0

.LBB0_999:
	v_cndmask_b32_e64 v174, v234, v174, s[100:101]
	v_cndmask_b32_e64 v175, v235, v175, s[100:101]
	v_cvt_f32_ubyte1_e32 v179, v174
	v_cvt_f32_ubyte0_e32 v178, v174
	v_cvt_f32_ubyte3_e32 v183, v174
	v_cvt_f32_ubyte2_e32 v182, v174
	v_cvt_f32_ubyte1_e32 v191, v175
	v_cvt_f32_ubyte0_e32 v190, v175
	v_cvt_f32_ubyte3_e32 v195, v175
	v_cvt_f32_ubyte2_e32 v194, v175
	s_and_b64 vcc, exec, s[6:7]
	s_mov_b64 s[26:27], -1
	s_cbranch_vccnz .LBB0_1001
	v_mov_b32_e32 v234, v160
	v_mov_b32_e32 v235, v161
	v_cvt_f32_ubyte0_e32 v143, v160
	v_cvt_f32_ubyte1_e32 v155, v160
	v_cvt_f32_ubyte2_e32 v157, v160
	v_cvt_f32_ubyte3_e32 v169, v160
	v_cvt_f32_ubyte0_e32 v170, v161
	v_cvt_f32_ubyte1_e32 v171, v161
	v_cvt_f32_ubyte2_e32 v174, v161
	v_cvt_f32_ubyte3_e32 v175, v161
	v_rcp_iflag_f32_e32 v160, v143
	v_rcp_iflag_f32_e32 v161, v155
	v_rcp_iflag_f32_e32 v168, v157
	v_rcp_iflag_f32_e32 v169, v169
	v_rcp_iflag_f32_e32 v170, v170
	v_rcp_iflag_f32_e32 v171, v171
	v_rcp_iflag_f32_e32 v186, v174
	v_rcp_iflag_f32_e32 v187, v175
	v_pk_mul_f32 v[196:197], v[160:161], v[178:179]
	v_pk_mul_f32 v[198:199], v[168:169], v[182:183]
	v_pk_mul_f32 v[174:175], v[170:171], v[190:191]
	v_pk_mul_f32 v[186:187], v[186:187], v[194:195]
	s_mov_b64 s[26:27], 0

.LBB0_1005:
	v_cndmask_b32_e64 v152, v236, v152, s[100:101]
	v_cndmask_b32_e64 v153, v237, v153, s[100:101]
	v_cvt_f32_ubyte1_e32 v161, v152
	v_cvt_f32_ubyte0_e32 v160, v152
	v_cvt_f32_ubyte3_e32 v175, v152
	v_cvt_f32_ubyte2_e32 v174, v152
	v_cvt_f32_ubyte1_e32 v179, v153
	v_cvt_f32_ubyte0_e32 v178, v153
	v_cvt_f32_ubyte3_e32 v187, v153
	v_cvt_f32_ubyte2_e32 v186, v153
	s_and_b64 vcc, exec, s[6:7]
	s_mov_b64 s[26:27], -1
	s_cbranch_vccnz .LBB0_1007
	v_mov_b32_e32 v236, v148
	v_mov_b32_e32 v237, v149
	v_cvt_f32_ubyte0_e32 v143, v148
	v_cvt_f32_ubyte1_e32 v152, v148
	v_cvt_f32_ubyte2_e32 v153, v148
	v_cvt_f32_ubyte3_e32 v155, v148
	v_cvt_f32_ubyte0_e32 v168, v149
	v_cvt_f32_ubyte1_e32 v169, v149
	v_cvt_f32_ubyte2_e32 v170, v149
	v_cvt_f32_ubyte3_e32 v171, v149
	v_rcp_iflag_f32_e32 v148, v143
	v_rcp_iflag_f32_e32 v149, v152
	v_rcp_iflag_f32_e32 v152, v153
	v_rcp_iflag_f32_e32 v153, v155
	v_rcp_iflag_f32_e32 v168, v168
	v_rcp_iflag_f32_e32 v169, v169
	v_rcp_iflag_f32_e32 v170, v170
	v_rcp_iflag_f32_e32 v171, v171
	v_pk_mul_f32 v[190:191], v[148:149], v[160:161]
	v_pk_mul_f32 v[194:195], v[152:153], v[174:175]
	v_pk_mul_f32 v[152:153], v[168:169], v[178:179]
	v_pk_mul_f32 v[182:183], v[170:171], v[186:187]
	s_mov_b64 s[26:27], 0

.LBB0_1011:
	v_add_u32_e32 v186, 0x80, v142
	v_mad_i64_i32 v[148:149], s[26:27], v186, s97, v[144:145]
	v_lshl_add_u64 v[148:149], v[148:149], 0, s[24:25]
	s_and_b64 vcc, exec, s[100:101]
	s_cbranch_vccz .Lcarry5_8
	global_load_dwordx2 v[194:195], v[148:149], off
.Lcarry5_8:
	v_mov_b32_e32 v178, 0
	s_and_b64 vcc, exec, s[6:7]
	v_mov_b32_e32 v190, 0
	v_mov_b32_e32 v191, 0
	s_cbranch_vccnz .LBB0_1013
	global_load_dwordx2 v[190:191], v[148:149], off offset:2048
.LBB0_1013:
	s_and_b64 vcc, exec, s[100:101]
	s_cbranch_vccz .Lcarry5_9
	global_load_dwordx2 v[182:183], v[148:149], off offset:128
.Lcarry5_9:
	s_and_b64 vcc, exec, s[6:7]
	v_mov_b32_e32 v179, 0
	s_cbranch_vccnz .LBB0_1015
	global_load_dwordx2 v[178:179], v[148:149], off offset:2176
.LBB0_1015:
	v_add_u32_e32 v156, 0x90, v142
	v_mad_i64_i32 v[148:149], s[26:27], v156, s97, v[144:145]
	v_lshl_add_u64 v[196:197], v[148:149], 0, s[24:25]
	s_and_b64 vcc, exec, s[100:101]
	s_cbranch_vccz .Lcarry5_10
	global_load_dwordx2 v[174:175], v[196:197], off
.Lcarry5_10:
	v_mov_b32_e32 v148, 0
	s_and_b64 vcc, exec, s[6:7]
	v_mov_b32_e32 v160, 0
	v_mov_b32_e32 v161, 0
	s_cbranch_vccnz .LBB0_1017
	global_load_dwordx2 v[160:161], v[196:197], off offset:2048
.LBB0_1017:
	s_and_b64 vcc, exec, s[100:101]
	s_cbranch_vccz .Lcarry5_11
	global_load_dwordx2 v[152:153], v[196:197], off offset:128
.Lcarry5_11:
	s_and_b64 vcc, exec, s[6:7]
	v_mov_b32_e32 v149, 0
	s_cbranch_vccnz .LBB0_1019
	global_load_dwordx2 v[148:149], v[196:197], off offset:2176
.LBB0_1019:
	v_cndmask_b32_e64 v192, v238, v192, s[100:101]
	v_cndmask_b32_e64 v193, v239, v193, s[100:101]
	v_cvt_f32_ubyte1_e32 v197, v192
	v_cvt_f32_ubyte0_e32 v196, v192
	v_cvt_f32_ubyte3_e32 v199, v192
	v_cvt_f32_ubyte2_e32 v198, v192
	v_cvt_f32_ubyte1_e32 v203, v193
	v_cvt_f32_ubyte0_e32 v202, v193
	v_cvt_f32_ubyte3_e32 v205, v193
	v_cvt_f32_ubyte2_e32 v204, v193
	s_mov_b64 s[26:27], -1
	s_and_b64 vcc, exec, s[22:23]
	s_cbranch_vccz .LBB0_1021
	v_mov_b32_e32 v238, v188
	v_mov_b32_e32 v239, v189
	v_cvt_f32_ubyte0_e32 v143, v188
	v_cvt_f32_ubyte1_e32 v155, v188
	v_cvt_f32_ubyte2_e32 v157, v188
	v_cvt_f32_ubyte3_e32 v171, v188
	v_cvt_f32_ubyte0_e32 v185, v189
	v_cvt_f32_ubyte1_e32 v187, v189
	v_cvt_f32_ubyte2_e32 v192, v189
	v_cvt_f32_ubyte3_e32 v193, v189
	v_rcp_iflag_f32_e32 v168, v143
	v_rcp_iflag_f32_e32 v169, v155
	v_rcp_iflag_f32_e32 v170, v157
	v_rcp_iflag_f32_e32 v171, v171
	v_rcp_iflag_f32_e32 v188, v185
	v_rcp_iflag_f32_e32 v189, v187
	v_rcp_iflag_f32_e32 v200, v192
	v_rcp_iflag_f32_e32 v201, v193
	v_pk_mul_f32 v[206:207], v[168:169], v[196:197]
	v_pk_mul_f32 v[208:209], v[170:171], v[198:199]
	v_pk_mul_f32 v[192:193], v[188:189], v[202:203]
	v_pk_mul_f32 v[200:201], v[200:201], v[204:205]
	s_mov_b64 s[26:27], 0

.LBB0_1025:
	v_cndmask_b32_e64 v180, v240, v180, s[100:101]
	v_cndmask_b32_e64 v181, v241, v181, s[100:101]
	v_cvt_f32_ubyte1_e32 v189, v180
	v_cvt_f32_ubyte0_e32 v188, v180
	v_cvt_f32_ubyte3_e32 v193, v180
	v_cvt_f32_ubyte2_e32 v192, v180
	v_cvt_f32_ubyte1_e32 v197, v181
	v_cvt_f32_ubyte0_e32 v196, v181
	v_cvt_f32_ubyte3_e32 v201, v181
	v_cvt_f32_ubyte2_e32 v200, v181
	s_and_b64 vcc, exec, s[6:7]
	s_mov_b64 s[26:27], -1
	s_cbranch_vccnz .LBB0_1027
	v_mov_b32_e32 v240, v176
	v_mov_b32_e32 v241, v177
	v_cvt_f32_ubyte0_e32 v143, v176
	v_cvt_f32_ubyte1_e32 v155, v176
	v_cvt_f32_ubyte2_e32 v157, v176
	v_cvt_f32_ubyte3_e32 v171, v176
	v_cvt_f32_ubyte0_e32 v176, v177
	v_cvt_f32_ubyte1_e32 v180, v177
	v_cvt_f32_ubyte2_e32 v181, v177
	v_cvt_f32_ubyte3_e32 v187, v177
	v_rcp_iflag_f32_e32 v168, v143
	v_rcp_iflag_f32_e32 v169, v155
	v_rcp_iflag_f32_e32 v170, v157
	v_rcp_iflag_f32_e32 v171, v171
	v_rcp_iflag_f32_e32 v176, v176
	v_rcp_iflag_f32_e32 v177, v180
	v_rcp_iflag_f32_e32 v198, v181
	v_rcp_iflag_f32_e32 v199, v187
	v_pk_mul_f32 v[202:203], v[168:169], v[188:189]
	v_pk_mul_f32 v[204:205], v[170:171], v[192:193]
	v_pk_mul_f32 v[180:181], v[176:177], v[196:197]
	v_pk_mul_f32 v[198:199], v[198:199], v[200:201]
	s_mov_b64 s[26:27], 0

.LBB0_1031:
	v_cndmask_b32_e64 v172, v242, v172, s[100:101]
	v_cndmask_b32_e64 v173, v243, v173, s[100:101]
	v_cvt_f32_ubyte1_e32 v177, v172
	v_cvt_f32_ubyte0_e32 v176, v172
	v_cvt_f32_ubyte3_e32 v181, v172
	v_cvt_f32_ubyte2_e32 v180, v172
	v_cvt_f32_ubyte1_e32 v189, v173
	v_cvt_f32_ubyte0_e32 v188, v173
	v_cvt_f32_ubyte3_e32 v193, v173
	v_cvt_f32_ubyte2_e32 v192, v173
	s_and_b64 vcc, exec, s[6:7]
	s_mov_b64 s[26:27], -1
	s_cbranch_vccnz .LBB0_1033
	v_mov_b32_e32 v242, v158
	v_mov_b32_e32 v243, v159
	v_cvt_f32_ubyte0_e32 v143, v158
	v_cvt_f32_ubyte1_e32 v155, v158
	v_cvt_f32_ubyte2_e32 v157, v158
	v_cvt_f32_ubyte3_e32 v169, v158
	v_cvt_f32_ubyte0_e32 v170, v159
	v_cvt_f32_ubyte1_e32 v171, v159
	v_cvt_f32_ubyte2_e32 v172, v159
	v_cvt_f32_ubyte3_e32 v173, v159
	v_rcp_iflag_f32_e32 v158, v143
	v_rcp_iflag_f32_e32 v159, v155
	v_rcp_iflag_f32_e32 v168, v157
	v_rcp_iflag_f32_e32 v169, v169
	v_rcp_iflag_f32_e32 v170, v170
	v_rcp_iflag_f32_e32 v171, v171
	v_rcp_iflag_f32_e32 v184, v172
	v_rcp_iflag_f32_e32 v185, v173
	v_pk_mul_f32 v[196:197], v[158:159], v[176:177]
	v_pk_mul_f32 v[198:199], v[168:169], v[180:181]
	v_pk_mul_f32 v[172:173], v[170:171], v[188:189]
	v_pk_mul_f32 v[184:185], v[184:185], v[192:193]
	s_mov_b64 s[26:27], 0

.LBB0_1037:
	v_cndmask_b32_e64 v150, v244, v150, s[100:101]
	v_cndmask_b32_e64 v151, v245, v151, s[100:101]
	v_cvt_f32_ubyte1_e32 v159, v150
	v_cvt_f32_ubyte0_e32 v158, v150
	v_cvt_f32_ubyte3_e32 v173, v150
	v_cvt_f32_ubyte2_e32 v172, v150
	v_cvt_f32_ubyte1_e32 v177, v151
	v_cvt_f32_ubyte0_e32 v176, v151
	v_cvt_f32_ubyte3_e32 v185, v151
	v_cvt_f32_ubyte2_e32 v184, v151
	s_and_b64 vcc, exec, s[6:7]
	s_mov_b64 s[26:27], -1
	s_cbranch_vccnz .LBB0_1039
	v_mov_b32_e32 v244, v146
	v_mov_b32_e32 v245, v147
	v_cvt_f32_ubyte0_e32 v143, v146
	v_cvt_f32_ubyte1_e32 v150, v146
	v_cvt_f32_ubyte2_e32 v151, v146
	v_cvt_f32_ubyte3_e32 v157, v146
	v_cvt_f32_ubyte0_e32 v168, v147
	v_cvt_f32_ubyte1_e32 v169, v147
	v_cvt_f32_ubyte2_e32 v170, v147
	v_cvt_f32_ubyte3_e32 v171, v147
	v_rcp_iflag_f32_e32 v146, v143
	v_rcp_iflag_f32_e32 v147, v150
	v_rcp_iflag_f32_e32 v150, v151
	v_rcp_iflag_f32_e32 v151, v157
	v_rcp_iflag_f32_e32 v168, v168
	v_rcp_iflag_f32_e32 v169, v169
	v_rcp_iflag_f32_e32 v170, v170
	v_rcp_iflag_f32_e32 v171, v171
	v_pk_mul_f32 v[188:189], v[146:147], v[158:159]
	v_pk_mul_f32 v[192:193], v[150:151], v[172:173]
	v_pk_mul_f32 v[150:151], v[168:169], v[176:177]
	v_pk_mul_f32 v[180:181], v[170:171], v[184:185]
	s_mov_b64 s[26:27], 0

.LBB0_1051:
	s_waitcnt vmcnt(7)
	v_cndmask_b32_e64 v194, v246, v194, s[100:101]
	v_cndmask_b32_e64 v195, v247, v195, s[100:101]
	v_cvt_f32_ubyte1_e32 v189, v194
	v_cvt_f32_ubyte0_e32 v188, v194
	v_cvt_f32_ubyte3_e32 v197, v194
	v_cvt_f32_ubyte2_e32 v196, v194
	v_cvt_f32_ubyte1_e32 v199, v195
	v_cvt_f32_ubyte0_e32 v198, v195
	v_cvt_f32_ubyte3_e32 v201, v195
	v_cvt_f32_ubyte2_e32 v200, v195
	s_mov_b64 s[24:25], -1
	s_and_b64 vcc, exec, s[22:23]
	s_cbranch_vccz .LBB0_1053
	v_mov_b32_e32 v246, v190
	v_mov_b32_e32 v247, v191
	v_cvt_f32_ubyte0_e32 v147, v190
	v_cvt_f32_ubyte1_e32 v157, v190
	v_cvt_f32_ubyte2_e32 v170, v190
	v_cvt_f32_ubyte3_e32 v171, v190
	v_cvt_f32_ubyte0_e32 v177, v191
	v_cvt_f32_ubyte1_e32 v187, v191
	v_cvt_f32_ubyte2_e32 v192, v191
	v_cvt_f32_ubyte3_e32 v193, v191
	v_rcp_iflag_f32_e32 v168, v147
	v_rcp_iflag_f32_e32 v169, v157
	v_rcp_iflag_f32_e32 v170, v170
	v_rcp_iflag_f32_e32 v171, v171
	v_rcp_iflag_f32_e32 v190, v177
	v_rcp_iflag_f32_e32 v191, v187
	v_rcp_iflag_f32_e32 v194, v192
	v_rcp_iflag_f32_e32 v195, v193
	v_pk_mul_f32 v[202:203], v[168:169], v[188:189]
	v_pk_mul_f32 v[204:205], v[170:171], v[196:197]
	v_pk_mul_f32 v[192:193], v[190:191], v[198:199]
	v_pk_mul_f32 v[194:195], v[194:195], v[200:201]
	s_mov_b64 s[24:25], 0

.LBB0_1057:
	s_waitcnt vmcnt(6)
	s_nop 0
	v_cndmask_b32_e64 v182, v248, v182, s[100:101]
	v_cndmask_b32_e64 v183, v249, v183, s[100:101]
	v_cvt_f32_ubyte1_e32 v189, v182
	v_cvt_f32_ubyte0_e32 v188, v182
	v_cvt_f32_ubyte3_e32 v191, v182
	v_cvt_f32_ubyte2_e32 v190, v182
	v_cvt_f32_ubyte1_e32 v193, v183
	v_cvt_f32_ubyte0_e32 v192, v183
	v_cvt_f32_ubyte3_e32 v197, v183
	v_cvt_f32_ubyte2_e32 v196, v183
	s_and_b64 vcc, exec, s[6:7]
	s_mov_b64 s[24:25], -1
	s_cbranch_vccnz .LBB0_1059
	v_mov_b32_e32 v248, v178
	v_mov_b32_e32 v249, v179
	v_cvt_f32_ubyte0_e32 v147, v178
	v_cvt_f32_ubyte1_e32 v157, v178
	v_cvt_f32_ubyte2_e32 v170, v178
	v_cvt_f32_ubyte3_e32 v171, v178
	v_cvt_f32_ubyte0_e32 v177, v179
	v_cvt_f32_ubyte1_e32 v182, v179
	v_cvt_f32_ubyte2_e32 v183, v179
	v_cvt_f32_ubyte3_e32 v195, v179
	v_rcp_iflag_f32_e32 v168, v147
	v_rcp_iflag_f32_e32 v169, v157
	v_rcp_iflag_f32_e32 v170, v170
	v_rcp_iflag_f32_e32 v171, v171
	v_rcp_iflag_f32_e32 v178, v177
	v_rcp_iflag_f32_e32 v179, v182
	v_rcp_iflag_f32_e32 v194, v183
	v_rcp_iflag_f32_e32 v195, v195
	v_pk_mul_f32 v[198:199], v[168:169], v[188:189]
	v_pk_mul_f32 v[200:201], v[170:171], v[190:191]
	v_pk_mul_f32 v[182:183], v[178:179], v[192:193]
	v_pk_mul_f32 v[194:195], v[194:195], v[196:197]
	s_mov_b64 s[24:25], 0

.LBB0_1063:
	s_waitcnt vmcnt(5)
	v_cndmask_b32_e64 v174, v250, v174, s[100:101]
	v_cndmask_b32_e64 v175, v251, v175, s[100:101]
	v_cvt_f32_ubyte1_e32 v179, v174
	v_cvt_f32_ubyte0_e32 v178, v174
	v_cvt_f32_ubyte3_e32 v183, v174
	v_cvt_f32_ubyte2_e32 v182, v174
	v_cvt_f32_ubyte1_e32 v189, v175
	v_cvt_f32_ubyte0_e32 v188, v175
	v_cvt_f32_ubyte3_e32 v191, v175
	v_cvt_f32_ubyte2_e32 v190, v175
	s_and_b64 vcc, exec, s[6:7]
	s_mov_b64 s[24:25], -1
	s_cbranch_vccnz .LBB0_1065
	v_mov_b32_e32 v250, v160
	v_mov_b32_e32 v251, v161
	v_cvt_f32_ubyte0_e32 v147, v160
	v_cvt_f32_ubyte1_e32 v157, v160
	v_cvt_f32_ubyte2_e32 v168, v160
	v_cvt_f32_ubyte3_e32 v169, v160
	v_cvt_f32_ubyte0_e32 v170, v161
	v_cvt_f32_ubyte1_e32 v171, v161
	v_cvt_f32_ubyte2_e32 v174, v161
	v_cvt_f32_ubyte3_e32 v175, v161
	v_rcp_iflag_f32_e32 v160, v147
	v_rcp_iflag_f32_e32 v161, v157
	v_rcp_iflag_f32_e32 v168, v168
	v_rcp_iflag_f32_e32 v169, v169
	v_rcp_iflag_f32_e32 v170, v170
	v_rcp_iflag_f32_e32 v171, v171
	v_rcp_iflag_f32_e32 v186, v174
	v_rcp_iflag_f32_e32 v187, v175
	v_pk_mul_f32 v[192:193], v[160:161], v[178:179]
	v_pk_mul_f32 v[194:195], v[168:169], v[182:183]
	v_pk_mul_f32 v[174:175], v[170:171], v[188:189]
	v_pk_mul_f32 v[186:187], v[186:187], v[190:191]
	s_mov_b64 s[24:25], 0

.LBB0_1069:
	s_waitcnt vmcnt(4)
	v_cndmask_b32_e64 v152, v252, v152, s[100:101]
	v_cndmask_b32_e64 v153, v253, v153, s[100:101]
	v_cvt_f32_ubyte1_e32 v161, v152
	v_cvt_f32_ubyte0_e32 v160, v152
	v_cvt_f32_ubyte3_e32 v175, v152
	v_cvt_f32_ubyte2_e32 v174, v152
	v_cvt_f32_ubyte1_e32 v179, v153
	v_cvt_f32_ubyte0_e32 v178, v153
	v_cvt_f32_ubyte3_e32 v187, v153
	v_cvt_f32_ubyte2_e32 v186, v153
	s_and_b64 vcc, exec, s[6:7]
	s_mov_b64 s[24:25], -1
	s_cbranch_vccnz .LBB0_1071
	v_mov_b32_e32 v252, v148
	v_mov_b32_e32 v253, v149
	v_cvt_f32_ubyte0_e32 v147, v148
	v_cvt_f32_ubyte1_e32 v152, v148
	v_cvt_f32_ubyte2_e32 v153, v148
	v_cvt_f32_ubyte3_e32 v168, v148
	v_cvt_f32_ubyte0_e32 v169, v149
	v_cvt_f32_ubyte1_e32 v170, v149
	v_cvt_f32_ubyte2_e32 v171, v149
	v_cvt_f32_ubyte3_e32 v177, v149
	v_rcp_iflag_f32_e32 v148, v147
	v_rcp_iflag_f32_e32 v149, v152
	v_rcp_iflag_f32_e32 v152, v153
	v_rcp_iflag_f32_e32 v153, v168
	v_rcp_iflag_f32_e32 v168, v169
	v_rcp_iflag_f32_e32 v169, v170
	v_rcp_iflag_f32_e32 v170, v171
	v_rcp_iflag_f32_e32 v171, v177
	v_pk_mul_f32 v[188:189], v[148:149], v[160:161]
	v_pk_mul_f32 v[190:191], v[152:153], v[174:175]
	v_pk_mul_f32 v[152:153], v[168:169], v[178:179]
	v_pk_mul_f32 v[182:183], v[170:171], v[186:187]
	s_mov_b64 s[24:25], 0

	.amdhsa_kernel _Z6mk_fwd4Args
		.amdhsa_group_segment_fixed_size 0
		.amdhsa_private_segment_fixed_size 0
		.amdhsa_kernarg_size 488
		.amdhsa_user_sgpr_count 2
		.amdhsa_user_sgpr_dispatch_ptr 0
		.amdhsa_user_sgpr_queue_ptr 0
		.amdhsa_user_sgpr_kernarg_segment_ptr 1
		.amdhsa_user_sgpr_dispatch_id 0
		.amdhsa_user_sgpr_kernarg_preload_length 0
		.amdhsa_user_sgpr_kernarg_preload_offset 0
		.amdhsa_user_sgpr_private_segment_size 0
		.amdhsa_uses_dynamic_stack 0
		.amdhsa_enable_private_segment 0
		.amdhsa_system_sgpr_workgroup_id_x 1
		.amdhsa_system_sgpr_workgroup_id_y 0
		.amdhsa_system_sgpr_workgroup_id_z 0
		.amdhsa_system_sgpr_workgroup_info 0
		.amdhsa_system_vgpr_workitem_id 0
		.amdhsa_next_free_vgpr 256
		.amdhsa_next_free_sgpr 102
		.amdhsa_accum_offset 256
		.amdhsa_reserve_vcc 1
		.amdhsa_float_round_mode_32 0
		.amdhsa_float_round_mode_16_64 0
		.amdhsa_float_denorm_mode_32 3
		.amdhsa_float_denorm_mode_16_64 3
		.amdhsa_dx10_clamp 1
		.amdhsa_ieee_mode 1
		.amdhsa_fp16_overflow 0
		.amdhsa_tg_split 0
		.amdhsa_exception_fp_ieee_invalid_op 0
		.amdhsa_exception_fp_denorm_src 0
		.amdhsa_exception_fp_ieee_div_zero 0
		.amdhsa_exception_fp_ieee_overflow 0
		.amdhsa_exception_fp_ieee_underflow 0
		.amdhsa_exception_fp_ieee_inexact 0
		.amdhsa_exception_int_div_zero 0
	.end_amdhsa_kernel

amdhsa.kernels:
  - .agpr_count:     0
    .args:
      - .offset:         0
        .size:           232
        .value_kind:     by_value
      - .offset:         232
        .size:           4
        .value_kind:     hidden_block_count_x
      - .offset:         236
        .size:           4
        .value_kind:     hidden_block_count_y
      - .offset:         240
        .size:           4
        .value_kind:     hidden_block_count_z
      - .offset:         244
        .size:           2
        .value_kind:     hidden_group_size_x
      - .offset:         246
        .size:           2
        .value_kind:     hidden_group_size_y
      - .offset:         248
        .size:           2
        .value_kind:     hidden_group_size_z
      - .offset:         250
        .size:           2
        .value_kind:     hidden_remainder_x
      - .offset:         252
        .size:           2
        .value_kind:     hidden_remainder_y
      - .offset:         254
        .size:           2
        .value_kind:     hidden_remainder_z
      - .offset:         272
        .size:           8
        .value_kind:     hidden_global_offset_x
      - .offset:         280
        .size:           8
        .value_kind:     hidden_global_offset_y
      - .offset:         288
        .size:           8
        .value_kind:     hidden_global_offset_z
      - .offset:         296
        .size:           2
        .value_kind:     hidden_grid_dims
      - .offset:         352
        .size:           4
        .value_kind:     hidden_dynamic_lds_size
    .group_segment_fixed_size: 0
    .kernarg_segment_align: 8
    .kernarg_segment_size: 488
    .language:       OpenCL C
    .language_version:
      - 2
      - 0
    .max_flat_workgroup_size: 512
    .name:           _Z6mk_fwd4Args
    .private_segment_fixed_size: 0
    .sgpr_count:     108
    .sgpr_spill_count: 111
    .symbol:         _Z6mk_fwd4Args.kd
    .uniform_work_group_size: 1
    .uses_dynamic_stack: false
    .vgpr_count:     256
    .vgpr_spill_count: 0
    .wavefront_size: 64
